# rd1 + workgroup barrier before the P1-tail transpose scratch writes (removes LDS overlap window with row prefetch buffers)
# baseline (speedup 1.0000x reference)
; #define LAS __attribute__((address_space(3)))
; template <bool MAP> __device__ __forceinline__ void p0_transpose_item(const float* W, int K, int NS, bf16* WT, LAS float* scr, int item, int nkb, int lane) {
;     const int pb = item / nkb, kb = item % nkb, k0 = 64 * kb, p0 = 32 * pb;
;     const int sc = MAP ? pg8::proj_src_col(p0 + (lane & 31)) : p0 + (lane & 31);
; #pragma unroll 8
;     for (int i = 0; i < 32; ++i) { const int kk = 2 * i + (lane >> 5); scr[kk * 33 + (lane & 31)] = W[(size_t)(k0 + kk) * NS + sc]; }
; template <int LO, int HI> __global__ void __launch_bounds__(NWAVES * 64, 2) fox_fwd(Args args) {
;     ...
;             for (int it = gw; it < 2048; it += NGW) p0_transpose_item<true>(w_in, D, INW, W1T, scr, it, D / 64, lane);
.LBB0_145:
	s_lshl_b32 s13, s10, 1
	s_lshl_b32 s14, s11, 1
	v_or_b32_e32 v17, s13, v1
	v_or_b32_e32 v34, s14, v2
	s_add_i32 s15, s13, 4
	s_add_i32 s16, s14, 4
	s_add_i32 s17, s13, 8
	s_add_i32 s20, s14, 8
	s_add_i32 s21, s13, 12
	s_add_i32 s26, s14, 12
	s_add_i32 s27, s13, 16
	s_add_i32 s28, s14, 16
	s_add_i32 s29, s13, 20
	s_add_i32 s30, s14, 20
	s_add_i32 s31, s13, 24
	s_add_i32 s34, s14, 24
	s_add_i32 s13, s13, 28
	s_add_i32 s14, s14, 28
	v_add_u32_e32 v18, s4, v34
	v_or_b32_e32 v52, s15, v1
	v_or_b32_e32 v53, s16, v2
	v_or_b32_e32 v54, s17, v1
	v_or_b32_e32 v55, s20, v2
	v_or_b32_e32 v56, s21, v1
	v_or_b32_e32 v57, s26, v2
	v_or_b32_e32 v58, s27, v1
	v_or_b32_e32 v59, s28, v2
	v_or_b32_e32 v60, s29, v1
	v_or_b32_e32 v61, s30, v2
	v_or_b32_e32 v62, s31, v1
	v_or_b32_e32 v63, s34, v2
	v_or_b32_e32 v64, s13, v1
	v_or_b32_e32 v65, s14, v2
	v_add_u32_e32 v19, s5, v17
	v_mul_lo_u32 v18, v18, s8
	v_add_u32_e32 v23, s5, v52
	v_add_u32_e32 v22, s4, v53
	v_add_u32_e32 v25, s5, v54
	v_add_u32_e32 v26, s4, v55
	v_add_u32_e32 v27, s5, v56
	v_add_u32_e32 v29, s4, v57
	v_add_u32_e32 v31, s5, v58
	v_add_u32_e32 v33, s4, v59
	v_add_u32_e32 v37, s5, v60
	v_add_u32_e32 v39, s4, v61
	v_add_u32_e32 v41, s5, v62
	v_add_u32_e32 v43, s4, v63
	v_add_u32_e32 v45, s5, v64
	v_add_u32_e32 v47, s4, v65
	v_mul_lo_u32 v20, v19, s8
	v_ashrrev_i32_e32 v19, 31, v18
	v_mul_lo_u32 v22, v22, s8
	v_mul_lo_u32 v24, v23, s8
	v_mul_lo_u32 v26, v26, s8
	v_mul_lo_u32 v28, v25, s8
	v_mul_lo_u32 v30, v29, s8
	v_mul_lo_u32 v32, v27, s8
	v_mul_lo_u32 v36, v33, s8
	v_mul_lo_u32 v38, v31, s8
	v_mul_lo_u32 v40, v39, s8
	v_mul_lo_u32 v42, v37, s8
	v_mul_lo_u32 v44, v43, s8
	v_mul_lo_u32 v46, v41, s8
	v_mul_lo_u32 v48, v47, s8
	v_mul_lo_u32 v50, v45, s8
	v_ashrrev_i32_e32 v21, 31, v20
	v_lshl_add_u64 v[18:19], v[18:19], 2, v[8:9]
	v_ashrrev_i32_e32 v25, 31, v24
	v_ashrrev_i32_e32 v23, 31, v22
	v_ashrrev_i32_e32 v29, 31, v28
	v_ashrrev_i32_e32 v27, 31, v26
	v_ashrrev_i32_e32 v33, 31, v32
	v_ashrrev_i32_e32 v31, 31, v30
	v_ashrrev_i32_e32 v39, 31, v38
	v_ashrrev_i32_e32 v37, 31, v36
	v_ashrrev_i32_e32 v43, 31, v42
	v_ashrrev_i32_e32 v41, 31, v40
	v_ashrrev_i32_e32 v47, 31, v46
	v_ashrrev_i32_e32 v45, 31, v44
	v_ashrrev_i32_e32 v51, 31, v50
	v_ashrrev_i32_e32 v49, 31, v48
	v_lshl_add_u64 v[20:21], v[20:21], 2, v[8:9]
	v_lshl_add_u64 v[22:23], v[22:23], 2, v[8:9]
	v_lshl_add_u64 v[24:25], v[24:25], 2, v[8:9]
	v_lshl_add_u64 v[26:27], v[26:27], 2, v[8:9]
	v_lshl_add_u64 v[28:29], v[28:29], 2, v[8:9]
	v_lshl_add_u64 v[30:31], v[30:31], 2, v[8:9]
	v_lshl_add_u64 v[32:33], v[32:33], 2, v[8:9]
	v_lshl_add_u64 v[36:37], v[36:37], 2, v[8:9]
	v_lshl_add_u64 v[38:39], v[38:39], 2, v[8:9]
	v_lshl_add_u64 v[40:41], v[40:41], 2, v[8:9]
	v_lshl_add_u64 v[42:43], v[42:43], 2, v[8:9]
	v_lshl_add_u64 v[44:45], v[44:45], 2, v[8:9]
	v_lshl_add_u64 v[46:47], v[46:47], 2, v[8:9]
	v_lshl_add_u64 v[48:49], v[48:49], 2, v[8:9]
	v_lshl_add_u64 v[50:51], v[50:51], 2, v[8:9]
	global_load_dword v66, v[18:19], off
	global_load_dword v67, v[20:21], off
	global_load_dword v69, v[22:23], off
	global_load_dword v70, v[24:25], off
	global_load_dword v71, v[26:27], off
	global_load_dword v72, v[28:29], off
	global_load_dword v73, v[30:31], off
	global_load_dword v74, v[32:33], off
	global_load_dword v75, v[36:37], off
	global_load_dword v76, v[38:39], off
	global_load_dword v77, v[40:41], off
	global_load_dword v78, v[42:43], off
	global_load_dword v79, v[44:45], off
	global_load_dword v80, v[46:47], off
	global_load_dword v81, v[48:49], off
	global_load_dword v82, v[50:51], off
	s_add_i32 s11, s11, 16
	s_add_i32 s10, s10, 16
	s_add_i32 s12, s12, -16
	v_mad_u64_u32 v[18:19], s[14:15], v34, s7, v[4:5]
	s_cmp_lg_u32 s12, 0
	v_mad_u64_u32 v[20:21], s[14:15], v17, s7, v[4:5]
	v_mad_u64_u32 v[22:23], s[14:15], v53, s7, v[4:5]
	v_mad_u64_u32 v[24:25], s[14:15], v52, s7, v[4:5]
	v_mad_u64_u32 v[26:27], s[14:15], v55, s7, v[4:5]
	v_mad_u64_u32 v[28:29], s[14:15], v54, s7, v[4:5]
	v_mad_u64_u32 v[30:31], s[14:15], v57, s7, v[4:5]
	v_mad_u64_u32 v[32:33], s[14:15], v56, s7, v[4:5]
	v_mad_u64_u32 v[36:37], s[14:15], v59, s7, v[4:5]
	v_mad_u64_u32 v[38:39], s[14:15], v58, s7, v[4:5]
	v_mad_u64_u32 v[40:41], s[14:15], v61, s7, v[4:5]
	v_mad_u64_u32 v[42:43], s[14:15], v60, s7, v[4:5]
	v_mad_u64_u32 v[44:45], s[14:15], v63, s7, v[4:5]
	v_mad_u64_u32 v[46:47], s[14:15], v62, s7, v[4:5]
	v_mad_u64_u32 v[48:49], s[14:15], v65, s7, v[4:5]
	v_mad_u64_u32 v[50:51], s[14:15], v64, s7, v[4:5]
	s_lshl_b32 s13, s10, 1
	s_lshl_b32 s14, s11, 1
	v_or_b32_e32 v187, s13, v1
	v_or_b32_e32 v204, s14, v2
	s_add_i32 s15, s13, 4
	s_add_i32 s16, s14, 4
	s_add_i32 s17, s13, 8
	s_add_i32 s20, s14, 8
	s_add_i32 s21, s13, 12
	s_add_i32 s26, s14, 12
	s_add_i32 s27, s13, 16
	s_add_i32 s28, s14, 16
	s_add_i32 s29, s13, 20
	s_add_i32 s30, s14, 20
	s_add_i32 s31, s13, 24
	s_add_i32 s34, s14, 24
	s_add_i32 s13, s13, 28
	s_add_i32 s14, s14, 28
	v_add_u32_e32 v188, s4, v204
	v_or_b32_e32 v222, s15, v1
	v_or_b32_e32 v223, s16, v2
	v_or_b32_e32 v224, s17, v1
	v_or_b32_e32 v225, s20, v2
	v_or_b32_e32 v226, s21, v1
	v_or_b32_e32 v227, s26, v2
	v_or_b32_e32 v228, s27, v1
	v_or_b32_e32 v229, s28, v2
	v_or_b32_e32 v230, s29, v1
	v_or_b32_e32 v231, s30, v2
	v_or_b32_e32 v232, s31, v1
	v_or_b32_e32 v233, s34, v2
	v_or_b32_e32 v234, s13, v1
	v_or_b32_e32 v235, s14, v2
	v_add_u32_e32 v189, s5, v187
	v_mul_lo_u32 v188, v188, s8
	v_add_u32_e32 v193, s5, v222
	v_add_u32_e32 v192, s4, v223
	v_add_u32_e32 v195, s5, v224
	v_add_u32_e32 v196, s4, v225
	v_add_u32_e32 v197, s5, v226
	v_add_u32_e32 v199, s4, v227
	v_add_u32_e32 v201, s5, v228
	v_add_u32_e32 v203, s4, v229
; template <bool MAP> __device__ __forceinline__ void p0_transpose_item(const float* W, int K, int NS, bf16* WT, LAS float* scr, int item, int nkb, int lane) {
;     ...
;     for (int i = 0; i < 32; ++i) { const int kk = 2 * i + (lane >> 5); scr[kk * 33 + (lane & 31)] = W[(size_t)(k0 + kk) * NS + sc]; }
	v_add_u32_e32 v207, s5, v230
	v_add_u32_e32 v209, s4, v231
	v_add_u32_e32 v211, s5, v232
	v_add_u32_e32 v213, s4, v233
	v_add_u32_e32 v215, s5, v234
	v_add_u32_e32 v217, s4, v235
	v_mul_lo_u32 v190, v189, s8
	v_ashrrev_i32_e32 v189, 31, v188
	v_mul_lo_u32 v192, v192, s8
	v_mul_lo_u32 v194, v193, s8
	v_mul_lo_u32 v196, v196, s8
	v_mul_lo_u32 v198, v195, s8
	v_mul_lo_u32 v200, v199, s8
	v_mul_lo_u32 v202, v197, s8
	v_mul_lo_u32 v206, v203, s8
	v_mul_lo_u32 v208, v201, s8
	v_mul_lo_u32 v210, v209, s8
	v_mul_lo_u32 v212, v207, s8
	v_mul_lo_u32 v214, v213, s8
	v_mul_lo_u32 v216, v211, s8
	v_mul_lo_u32 v218, v217, s8
	v_mul_lo_u32 v220, v215, s8
	v_ashrrev_i32_e32 v191, 31, v190
	v_lshl_add_u64 v[188:189], v[188:189], 2, v[8:9]
	v_ashrrev_i32_e32 v195, 31, v194
	v_ashrrev_i32_e32 v193, 31, v192
	v_ashrrev_i32_e32 v199, 31, v198
	v_ashrrev_i32_e32 v197, 31, v196
	v_ashrrev_i32_e32 v203, 31, v202
	v_ashrrev_i32_e32 v201, 31, v200
	v_ashrrev_i32_e32 v209, 31, v208
	v_ashrrev_i32_e32 v207, 31, v206
	v_ashrrev_i32_e32 v213, 31, v212
	v_ashrrev_i32_e32 v211, 31, v210
	v_ashrrev_i32_e32 v217, 31, v216
	v_ashrrev_i32_e32 v215, 31, v214
	v_ashrrev_i32_e32 v221, 31, v220
	v_ashrrev_i32_e32 v219, 31, v218
	v_lshl_add_u64 v[190:191], v[190:191], 2, v[8:9]
	v_lshl_add_u64 v[192:193], v[192:193], 2, v[8:9]
	v_lshl_add_u64 v[194:195], v[194:195], 2, v[8:9]
	v_lshl_add_u64 v[196:197], v[196:197], 2, v[8:9]
	v_lshl_add_u64 v[198:199], v[198:199], 2, v[8:9]
	v_lshl_add_u64 v[200:201], v[200:201], 2, v[8:9]
	v_lshl_add_u64 v[202:203], v[202:203], 2, v[8:9]
	v_lshl_add_u64 v[206:207], v[206:207], 2, v[8:9]
	v_lshl_add_u64 v[208:209], v[208:209], 2, v[8:9]
	v_lshl_add_u64 v[210:211], v[210:211], 2, v[8:9]
	v_lshl_add_u64 v[212:213], v[212:213], 2, v[8:9]
	v_lshl_add_u64 v[214:215], v[214:215], 2, v[8:9]
	v_lshl_add_u64 v[216:217], v[216:217], 2, v[8:9]
	v_lshl_add_u64 v[218:219], v[218:219], 2, v[8:9]
	v_lshl_add_u64 v[220:221], v[220:221], 2, v[8:9]
	global_load_dword v236, v[188:189], off
	global_load_dword v237, v[190:191], off
	global_load_dword v239, v[192:193], off
	global_load_dword v240, v[194:195], off
	global_load_dword v241, v[196:197], off
	global_load_dword v242, v[198:199], off
	global_load_dword v243, v[200:201], off
	global_load_dword v244, v[202:203], off
	global_load_dword v245, v[206:207], off
	global_load_dword v246, v[208:209], off
	global_load_dword v247, v[210:211], off
	global_load_dword v248, v[212:213], off
	global_load_dword v249, v[214:215], off
	global_load_dword v250, v[216:217], off
	global_load_dword v251, v[218:219], off
	global_load_dword v252, v[220:221], off
	s_barrier
; #define GAS __attribute__((address_space(1)))
; #define LAS __attribute__((address_space(3)))
; #define LDS_WAIT() asm volatile("s_waitcnt lgkmcnt(0)" ::: "memory")
; __device__ __forceinline__ unsigned pk2(float lo, float hi) { return pg8::cvt_pk_bf16(lo, hi); }
; template <bool MAP> __device__ __forceinline__ void p0_transpose_item(const float* W, int K, int NS, bf16* WT, LAS float* scr, int item, int nkb, int lane) {
;     ...
;     for (int i = 0; i < 32; ++i) { const int kk = 2 * i + (lane >> 5); scr[kk * 33 + (lane & 31)] = W[(size_t)(k0 + kk) * NS + sc]; }
;     LDS_WAIT(); asm volatile("" ::: "memory");
;     const int c = lane & 7;
; #pragma unroll
;     for (int j = 0; j < 4; ++j) { const int n = (lane >> 3) + 8 * j; const LAS float* s = scr + (8 * c) * 33 + n;
;         v4u o; o.x = pk2(s[0 * 33], s[1 * 33]); o.y = pk2(s[2 * 33], s[3 * 33]); o.z = pk2(s[4 * 33], s[5 * 33]); o.w = pk2(s[6 * 33], s[7 * 33]);
;         *(GAS v4u*)(WT + (size_t)(p0 + n) * K + k0 + 8 * c) = o; }
;     LDS_WAIT(); asm volatile("" ::: "memory");
; template <int LO, int HI> __global__ void __launch_bounds__(NWAVES * 64, 2) fox_fwd(Args args) {
;     ...
;             for (int it = gw; it < 2048; it += NGW) p0_transpose_item<true>(w_in, D, INW, W1T, scr, it, D / 64, lane);
	s_waitcnt vmcnt(31)
	ds_write_b32 v18, v66 offset:32768
	s_waitcnt vmcnt(30)
	ds_write_b32 v20, v67 offset:32768
	s_waitcnt vmcnt(29)
	ds_write_b32 v22, v69 offset:32768
	s_waitcnt vmcnt(28)
	ds_write_b32 v24, v70 offset:32768
	s_waitcnt vmcnt(27)
	ds_write_b32 v26, v71 offset:32768
	s_waitcnt vmcnt(26)
	ds_write_b32 v28, v72 offset:32768
	s_waitcnt vmcnt(25)
	ds_write_b32 v30, v73 offset:32768
	s_waitcnt vmcnt(24)
	ds_write_b32 v32, v74 offset:32768
	s_waitcnt vmcnt(23)
	ds_write_b32 v36, v75 offset:32768
	s_waitcnt vmcnt(22)
	ds_write_b32 v38, v76 offset:32768
	s_waitcnt vmcnt(21)
	ds_write_b32 v40, v77 offset:32768
	s_waitcnt vmcnt(20)
	ds_write_b32 v42, v78 offset:32768
	s_waitcnt vmcnt(19)
	ds_write_b32 v44, v79 offset:32768
	s_waitcnt vmcnt(18)
	ds_write_b32 v46, v80 offset:32768
	s_waitcnt vmcnt(17)
	ds_write_b32 v48, v81 offset:32768
	s_waitcnt vmcnt(16)
	ds_write_b32 v50, v82 offset:32768
	s_add_i32 s11, s11, 16
	s_add_i32 s10, s10, 16
	s_add_i32 s12, s12, -16
	v_mad_u64_u32 v[18:19], s[14:15], v204, s7, v[4:5]
	s_cmp_lg_u32 s12, 0
	v_mad_u64_u32 v[20:21], s[14:15], v187, s7, v[4:5]
	v_mad_u64_u32 v[22:23], s[14:15], v223, s7, v[4:5]
	v_mad_u64_u32 v[24:25], s[14:15], v222, s7, v[4:5]
	v_mad_u64_u32 v[26:27], s[14:15], v225, s7, v[4:5]
	v_mad_u64_u32 v[28:29], s[14:15], v224, s7, v[4:5]
	v_mad_u64_u32 v[30:31], s[14:15], v227, s7, v[4:5]
	v_mad_u64_u32 v[32:33], s[14:15], v226, s7, v[4:5]
	v_mad_u64_u32 v[36:37], s[14:15], v229, s7, v[4:5]
	v_mad_u64_u32 v[38:39], s[14:15], v228, s7, v[4:5]
	v_mad_u64_u32 v[40:41], s[14:15], v231, s7, v[4:5]
	v_mad_u64_u32 v[42:43], s[14:15], v230, s7, v[4:5]
	v_mad_u64_u32 v[44:45], s[14:15], v233, s7, v[4:5]
	v_mad_u64_u32 v[46:47], s[14:15], v232, s7, v[4:5]
	v_mad_u64_u32 v[48:49], s[14:15], v235, s7, v[4:5]
	v_mad_u64_u32 v[50:51], s[14:15], v234, s7, v[4:5]
	s_waitcnt vmcnt(15)
	ds_write_b32 v18, v236 offset:32768
	s_waitcnt vmcnt(14)
	ds_write_b32 v20, v237 offset:32768
	s_waitcnt vmcnt(13)
	ds_write_b32 v22, v239 offset:32768
	s_waitcnt vmcnt(12)
	ds_write_b32 v24, v240 offset:32768
	s_waitcnt vmcnt(11)
	ds_write_b32 v26, v241 offset:32768
	s_waitcnt vmcnt(10)
	ds_write_b32 v28, v242 offset:32768
	s_waitcnt vmcnt(9)
	ds_write_b32 v30, v243 offset:32768
	s_waitcnt vmcnt(8)
	ds_write_b32 v32, v244 offset:32768
	s_waitcnt vmcnt(7)
	ds_write_b32 v36, v245 offset:32768
	s_waitcnt vmcnt(6)
	ds_write_b32 v38, v246 offset:32768
	s_waitcnt vmcnt(5)
	ds_write_b32 v40, v247 offset:32768
	s_waitcnt vmcnt(4)
	ds_write_b32 v42, v248 offset:32768
	s_waitcnt vmcnt(3)
	ds_write_b32 v44, v249 offset:32768
	s_waitcnt vmcnt(2)
	ds_write_b32 v46, v250 offset:32768
	s_waitcnt vmcnt(1)
	ds_write_b32 v48, v251 offset:32768
	s_waitcnt vmcnt(0)
	ds_write_b32 v50, v252 offset:32768
	s_waitcnt lgkmcnt(0)
	v_add_u32_e32 v17, 0x8000, v13
	v_or_b32_e32 v22, s9, v12
	ds_read2_b32 v[66:67], v17 offset1:33
	ds_read2_b32 v[70:71], v17 offset0:66 offset1:99
	ds_read2_b32 v[72:73], v17 offset0:132 offset1:165
	ds_read2_b32 v[74:75], v17 offset0:198 offset1:231
	ds_read2_b32 v[76:77], v17 offset0:8 offset1:41
	ds_read2_b32 v[78:79], v17 offset0:74 offset1:107
	ds_read2_b32 v[80:81], v17 offset0:140 offset1:173
	ds_read2_b32 v[236:237], v17 offset0:206 offset1:239
	s_ashr_i32 s5, s4, 31
	v_ashrrev_i32_e32 v23, 31, v22
	s_waitcnt lgkmcnt(7)
	v_cvt_pk_bf16_f32 v18, v66, v67
	ds_read2_b32 v[66:67], v17 offset0:16 offset1:49
	v_lshl_add_u64 v[24:25], s[4:5], 1, v[6:7]
	v_lshlrev_b64 v[22:23], 11, v[22:23]
	s_waitcnt lgkmcnt(7)
	v_cvt_pk_bf16_f32 v19, v70, v71
	ds_read2_b32 v[70:71], v17 offset0:82 offset1:115
	v_lshl_add_u64 v[22:23], v[24:25], 0, v[22:23]
	s_waitcnt lgkmcnt(7)
	v_cvt_pk_bf16_f32 v20, v72, v73
	ds_read2_b32 v[72:73], v17 offset0:148 offset1:181
	s_waitcnt lgkmcnt(7)
	v_cvt_pk_bf16_f32 v21, v74, v75
	ds_read2_b32 v[74:75], v17 offset0:214 offset1:247
	global_store_dwordx4 v[22:23], v[18:21], off
	v_or_b32_e32 v22, s9, v14
	v_ashrrev_i32_e32 v23, 31, v22
	s_waitcnt lgkmcnt(7)
	v_cvt_pk_bf16_f32 v18, v76, v77
	ds_read2_b32 v[76:77], v17 offset0:24 offset1:57
	v_lshlrev_b64 v[22:23], 11, v[22:23]
	s_waitcnt lgkmcnt(7)
	v_cvt_pk_bf16_f32 v19, v78, v79
	ds_read2_b32 v[78:79], v17 offset0:90 offset1:123
	v_lshl_add_u64 v[22:23], v[24:25], 0, v[22:23]
	s_waitcnt lgkmcnt(7)
	v_cvt_pk_bf16_f32 v20, v80, v81
	ds_read2_b32 v[80:81], v17 offset0:156 offset1:189
	s_waitcnt lgkmcnt(7)
	v_cvt_pk_bf16_f32 v21, v236, v237
	ds_read2_b32 v[236:237], v17 offset0:222 offset1:255
	global_store_dwordx4 v[22:23], v[18:21], off
	v_or_b32_e32 v22, s9, v15
	v_ashrrev_i32_e32 v23, 31, v22
	s_waitcnt lgkmcnt(7)
	v_cvt_pk_bf16_f32 v18, v66, v67
	v_lshlrev_b64 v[22:23], 11, v[22:23]
	s_waitcnt lgkmcnt(6)
	v_cvt_pk_bf16_f32 v19, v70, v71
	v_lshl_add_u64 v[22:23], v[24:25], 0, v[22:23]
	s_waitcnt lgkmcnt(5)
	v_cvt_pk_bf16_f32 v20, v72, v73
	s_waitcnt lgkmcnt(4)
	v_cvt_pk_bf16_f32 v21, v74, v75
	global_store_dwordx4 v[22:23], v[18:21], off
	v_or_b32_e32 v22, s9, v16
	v_ashrrev_i32_e32 v23, 31, v22
	s_waitcnt lgkmcnt(3)
	v_cvt_pk_bf16_f32 v18, v76, v77
	v_lshlrev_b64 v[22:23], 11, v[22:23]
	s_waitcnt lgkmcnt(2)
	v_cvt_pk_bf16_f32 v19, v78, v79
	v_lshl_add_u64 v[22:23], v[24:25], 0, v[22:23]
	s_waitcnt lgkmcnt(1)
	v_cvt_pk_bf16_f32 v20, v80, v81
	s_waitcnt lgkmcnt(0)
	v_cvt_pk_bf16_f32 v21, v236, v237
	global_store_dwordx4 v[22:23], v[18:21], off
	s_waitcnt lgkmcnt(0)
	s_add_i32 s33, s33, s6
	s_cmpk_gt_i32 s33, 0x7ff
	s_cbranch_scc0 .LBB0_136
